# attention softmax: half-wave max/sum exchange by v_permlane32_swap instead of ds_bpermute LDS round trips (bit-identical)
# speedup vs baseline: 1.0067x; 1.0030x over previous
; #define LAS __attribute__((address_space(3)))
; __device__ __forceinline__ void dsa_attn_unit(const Ctx& c, int l, int b, int kvh, int qb64) {
;     ...
;         for (int sub = 0; sub < 2; ++sub) {
;             const unsigned mwd = mw[sub];
;             if (__ballot(mwd != 0u) == 0ull) continue;
;             f32x16 acc;
; #pragma unroll
;             for (int v = 0; v < 16; ++v) acc[v] = 0.f;
;             const LAS unsigned char* kp = Kt + bi * 17408 + (sub * 32 + n) * 272 + hf * 16;
;             bf16x8 Kf[8];
; #pragma unroll
;             for (int ks = 0; ks < 8; ++ks) Kf[ks] = *(const LAS bf16x8*)(kp + ks * 32);
;             __builtin_amdgcn_sched_barrier(0);
; #pragma unroll
;             for (int ks = 0; ks < 8; ++ks) acc = __builtin_amdgcn_mfma_f32_32x32x16_bf16(Kf[ks], Qf[ks], acc, 0, 0, 0);
;             bf16x8 Vf[8];
; #pragma unroll
;             for (int mt = 0; mt < 4; ++mt)
; #pragma unroll
;                 for (int s2 = 0; s2 < 2; ++s2) {
;                     const int xr = 4 * (4 * mt + (n >> 3)), kb = sub * 32 + 16 * s2 + 4 * hf;
;                     const LAS unsigned char* vrow = VT + bi * 20480 + (32 * mt + n) * 160;
;                     const u32x2 lo = *(const LAS u32x2*)(vrow + (kb ^ xr) * 2), hi = *(const LAS u32x2*)(vrow + ((kb + 8) ^ xr) * 2);
;                     const u32x4 t = {lo.x, lo.y, hi.x, hi.y};
;                     Vf[mt * 2 + s2] = __builtin_bit_cast(bf16x8, t);
;                 }
;             __builtin_amdgcn_sched_barrier(0);
;             const unsigned wsh = mwd >> (4 * hf);
;             float mx = -INFINITY;
; #pragma unroll
;             for (int v = 0; v < 16; ++v) { const bool selv = (wsh >> ((v & 3) + 8 * (v >> 2))) & 1u; acc[v] = selv ? acc[v] * 0.12751743f : -INFINITY; mx = fmaxf(mx, acc[v]); }
;             mx = fmaxf(mx, lane_get(mx, lane ^ 32));
;             const float m_new = fmaxf(m_run, mx);
;             const float alpha = __builtin_amdgcn_exp2f(m_run - m_new);
;             float rs = 0.f;
; #pragma unroll
;             for (int v = 0; v < 16; ++v) { acc[v] = __builtin_amdgcn_exp2f(acc[v] - m_new); rs += acc[v]; }
;             rs += lane_get(rs, lane ^ 32);
;             l_run = l_run * alpha + rs; m_run = m_new;
;             if (__ballot(alpha != 1.0f) != 0ull) {
.LBB0_1442:
	s_and_b32 s9, s7, 1
	s_mul_i32 s18, s9, 0x4400
	s_mul_i32 s58, s9, 0x5000
	v_add_u32_e32 v64, s18, v185
	v_add_u32_e32 v225, s58, v163
	v_add_u32_e32 v226, v64, v187
	v_add_u32_e32 v224, v225, v188
	v_cmp_ne_u32_e32 vcc, 0, v174
	s_cbranch_vccz .LBB0_1449
	ds_read_b128 v[64:67], v226
	ds_read_b128 v[128:131], v226 offset:32
	ds_read_b128 v[132:135], v226 offset:64
	ds_read_b128 v[136:139], v226 offset:96
	ds_read_b128 v[140:143], v226 offset:128
	ds_read_b128 v[144:147], v226 offset:160
	ds_read_b128 v[156:159], v226 offset:192
	ds_read_b128 v[228:231], v226 offset:224
	s_waitcnt lgkmcnt(7)
	v_mfma_f32_32x32x16_bf16 v[64:79], v[64:67], v[104:107], 0
	v_add_u32_e32 v148, v224, v198
	v_add_u32_e32 v149, v224, v199
	s_waitcnt lgkmcnt(6)
	v_mfma_f32_32x32x16_bf16 v[64:79], v[128:131], v[80:83], v[64:79]
	v_add_u32_e32 v128, v224, v189
	v_add_u32_e32 v129, v224, v190
	v_add_u32_e32 v130, v224, v191
	v_add_u32_e32 v131, v224, v193
	s_waitcnt lgkmcnt(5)
	v_mfma_f32_32x32x16_bf16 v[64:79], v[132:135], v[84:87], v[64:79]
	ds_read_b64 v[132:133], v128
	ds_read_b64 v[134:135], v129
	ds_read_b64 v[128:129], v130
	ds_read_b64 v[130:131], v131
	s_waitcnt lgkmcnt(8)
	v_mfma_f32_32x32x16_bf16 v[64:79], v[136:139], v[88:91], v[64:79]
	v_add_u32_e32 v136, v224, v194
	v_add_u32_e32 v137, v224, v195
	v_add_u32_e32 v138, v224, v196
	v_add_u32_e32 v139, v224, v197
	s_waitcnt lgkmcnt(7)
	v_mfma_f32_32x32x16_bf16 v[64:79], v[140:143], v[92:95], v[64:79]
	ds_read_b64 v[140:141], v136 offset:5120
	ds_read_b64 v[142:143], v137 offset:5120
	ds_read_b64 v[136:137], v138 offset:5120
	ds_read_b64 v[138:139], v139 offset:5120
	s_waitcnt lgkmcnt(10)
	v_mfma_f32_32x32x16_bf16 v[64:79], v[144:147], v[96:99], v[64:79]
	v_add_u32_e32 v144, v224, v200
	v_add_u32_e32 v145, v224, v201
	ds_read_b64 v[152:153], v148 offset:10240
	ds_read_b64 v[154:155], v149 offset:10240
	ds_read_b64 v[148:149], v144 offset:10240
	ds_read_b64 v[150:151], v145 offset:10240
	v_add_u32_e32 v144, v224, v202
	v_add_u32_e32 v145, v224, v203
	v_add_u32_e32 v146, v224, v204
	v_add_u32_e32 v147, v224, v205
	s_waitcnt lgkmcnt(13)
	v_mfma_f32_32x32x16_bf16 v[64:79], v[156:159], v[100:103], v[64:79]
	ds_read_b64 v[156:157], v144 offset:15360
	ds_read_b64 v[158:159], v145 offset:15360
	ds_read_b64 v[144:145], v146 offset:15360
	ds_read_b64 v[146:147], v147 offset:15360
	s_waitcnt lgkmcnt(14)
	v_mfma_f32_32x32x16_bf16 v[64:79], v[228:231], v[108:111], v[64:79]
	v_lshrrev_b32_e32 v174, v168, v174
	v_and_b32_e32 v227, 1, v174
	s_nop 9
	v_mul_f32_e32 v64, 0x3e0293ee, v64
	v_cmp_eq_u32_e32 vcc, 1, v227
	v_and_b32_e32 v227, 2, v174
	v_mul_f32_e32 v65, 0x3e0293ee, v65
	v_cndmask_b32_e32 v64, v180, v64, vcc
	v_cmp_ne_u32_e32 vcc, 0, v227
	v_and_b32_e32 v228, 4, v174
	v_mul_f32_e32 v66, 0x3e0293ee, v66
	v_cndmask_b32_e32 v65, v180, v65, vcc
	v_cmp_ne_u32_e32 vcc, 0, v228
	v_max3_f32 v227, v64, s82, v65
	v_mul_f32_e32 v68, 0x3e0293ee, v68
	v_cndmask_b32_e32 v228, v180, v66, vcc
	v_mul_f32_e32 v66, 0x3e0293ee, v67
	v_and_b32_e32 v67, 8, v174
	v_cmp_ne_u32_e32 vcc, 0, v67
	s_nop 1
	v_cndmask_b32_e32 v67, v180, v66, vcc
	v_max3_f32 v66, v227, v228, v67
	v_and_b32_e32 v227, 0x100, v174
	v_cmp_ne_u32_e32 vcc, 0, v227
	s_nop 1
	v_cndmask_b32_e32 v227, v180, v68, vcc
	v_mul_f32_e32 v68, 0x3e0293ee, v69
	v_and_b32_e32 v69, 0x200, v174
	v_cmp_ne_u32_e32 vcc, 0, v69
	v_and_b32_e32 v69, 0x400, v174
	s_nop 0
	v_cndmask_b32_e32 v229, v180, v68, vcc
	v_mul_f32_e32 v68, 0x3e0293ee, v70
	v_cmp_ne_u32_e32 vcc, 0, v69
	v_and_b32_e32 v69, 0x800, v174
	v_max3_f32 v66, v66, v227, v229
	v_cndmask_b32_e32 v70, v180, v68, vcc
	v_mul_f32_e32 v68, 0x3e0293ee, v71
	v_cmp_ne_u32_e32 vcc, 0, v69
	v_and_b32_e32 v69, 0x10000, v174
	s_nop 0
	v_cndmask_b32_e32 v230, v180, v68, vcc
	v_mul_f32_e32 v68, 0x3e0293ee, v72
	v_cmp_ne_u32_e32 vcc, 0, v69
	v_and_b32_e32 v69, 0x20000, v174
	v_max3_f32 v66, v66, v70, v230
	v_cndmask_b32_e32 v231, v180, v68, vcc
	v_mul_f32_e32 v68, 0x3e0293ee, v73
	v_cmp_ne_u32_e32 vcc, 0, v69
	v_and_b32_e32 v69, 0x40000, v174
	s_nop 0
	v_cndmask_b32_e32 v73, v180, v68, vcc
	v_mul_f32_e32 v68, 0x3e0293ee, v74
	v_cmp_ne_u32_e32 vcc, 0, v69
	v_and_b32_e32 v69, 0x80000, v174
	v_max3_f32 v66, v66, v231, v73
	v_cndmask_b32_e32 v74, v180, v68, vcc
	v_mul_f32_e32 v68, 0x3e0293ee, v75
	v_cmp_ne_u32_e32 vcc, 0, v69
	v_and_b32_e32 v69, 0x1000000, v174
	s_nop 0
	v_cndmask_b32_e32 v75, v180, v68, vcc
	v_mul_f32_e32 v68, 0x3e0293ee, v76
	v_cmp_ne_u32_e32 vcc, 0, v69
	v_and_b32_e32 v69, 0x2000000, v174
	v_max3_f32 v66, v66, v74, v75
	v_cndmask_b32_e32 v76, v180, v68, vcc
	v_mul_f32_e32 v68, 0x3e0293ee, v77
	v_cmp_ne_u32_e32 vcc, 0, v69
	v_and_b32_e32 v69, 0x4000000, v174
	s_nop 0
	v_cndmask_b32_e32 v232, v180, v68, vcc
	v_mul_f32_e32 v68, 0x3e0293ee, v78
	v_cmp_ne_u32_e32 vcc, 0, v69
	v_and_b32_e32 v69, 0x8000000, v174
	v_max3_f32 v66, v66, v76, v232
	v_cndmask_b32_e32 v233, v180, v68, vcc
	v_mul_f32_e32 v68, 0x3e0293ee, v79
	v_cmp_ne_u32_e32 vcc, 0, v69
	s_nop 1
	v_cndmask_b32_e32 v234, v180, v68, vcc
	v_max3_f32 v66, v66, v233, v234
	v_mov_b32_e32 v68, v66
	v_mov_b32_e32 v238, v66
	s_nop 1
	v_permlane32_swap_b32_e32 v68, v238
	s_waitcnt lgkmcnt(0)
	v_max3_f32 v174, v223, v68, v238
	v_sub_f32_e32 v64, v64, v174
	v_exp_f32_e32 v66, v64
	v_sub_f32_e32 v65, v65, v174
	v_exp_f32_e32 v68, v65
	v_sub_f32_e32 v65, v228, v174
	v_exp_f32_e32 v69, v65
	v_sub_f32_e32 v65, v67, v174
	v_exp_f32_e32 v71, v65
	v_sub_f32_e32 v65, v227, v174
	v_add_f32_e32 v77, 0, v66
	v_exp_f32_e32 v72, v65
	v_add_f32_e32 v65, v68, v77
	v_add_f32_e32 v65, v69, v65
	v_add_f32_e32 v65, v71, v65
	v_add_f32_e32 v67, v72, v65
	v_sub_f32_e32 v65, v229, v174
	v_exp_f32_e32 v77, v65
	v_sub_f32_e32 v65, v70, v174
	v_exp_f32_e32 v78, v65
	v_sub_f32_e32 v65, v230, v174
	v_sub_f32_e32 v64, v223, v174
	v_exp_f32_e32 v223, v65
	v_sub_f32_e32 v65, v231, v174
	v_exp_f32_e32 v65, v65
	v_add_f32_e32 v67, v77, v67
	v_add_f32_e32 v67, v78, v67
	v_add_f32_e32 v67, v223, v67
	v_add_f32_e32 v79, v65, v67
	v_sub_f32_e32 v67, v73, v174
	v_exp_f32_e32 v67, v67
	v_sub_f32_e32 v70, v74, v174
	v_exp_f32_e32 v70, v70
	v_sub_f32_e32 v73, v75, v174
	v_exp_f32_e32 v73, v73
	v_sub_f32_e32 v74, v76, v174
	v_exp_f32_e32 v74, v74
	v_sub_f32_e32 v76, v232, v174
	v_add_f32_e32 v75, v67, v79
	v_exp_f32_e32 v79, v76
	v_sub_f32_e32 v76, v233, v174
	v_add_f32_e32 v75, v70, v75
	v_exp_f32_e32 v227, v76
	v_sub_f32_e32 v76, v234, v174
	v_add_f32_e32 v75, v73, v75
	v_exp_f32_e32 v228, v76
	v_add_f32_e32 v75, v74, v75
	v_add_f32_e32 v75, v79, v75
	v_add_f32_e32 v75, v227, v75
	v_add_f32_e32 v75, v228, v75
	v_exp_f32_e32 v64, v64
	v_mov_b32_e32 v76, v75
	v_mov_b32_e32 v239, v75
	s_nop 1
	v_permlane32_swap_b32_e32 v76, v239
	v_cmp_neq_f32_e32 vcc, 1.0, v64
	s_cbranch_vccz .LBB0_1445
; __device__ __forceinline__ unsigned cvt_pk_bf16(float lo, float hi) { unsigned r; asm volatile("v_cvt_pk_bf16_f32 %0, %1, %2" : "=v"(r) : "v"(lo), "v"(hi)); return r; }
; #define LAS __attribute__((address_space(3)))
; __device__ __forceinline__ void dsa_attn_unit(const Ctx& c, int l, int b, int kvh, int qb64) {
;     ...
;             const LAS unsigned char* kp = Kt + bi * 17408 + (sub * 32 + n) * 272 + hf * 16;
;             bf16x8 Kf[8];
; #pragma unroll
;             for (int ks = 0; ks < 8; ++ks) Kf[ks] = *(const LAS bf16x8*)(kp + ks * 32);
;             __builtin_amdgcn_sched_barrier(0);
; #pragma unroll
;             for (int ks = 0; ks < 8; ++ks) acc = __builtin_amdgcn_mfma_f32_32x32x16_bf16(Kf[ks], Qf[ks], acc, 0, 0, 0);
;             bf16x8 Vf[8];
; #pragma unroll
;             for (int mt = 0; mt < 4; ++mt)
; #pragma unroll
;                 for (int s2 = 0; s2 < 2; ++s2) {
;                     const int xr = 4 * (4 * mt + (n >> 3)), kb = sub * 32 + 16 * s2 + 4 * hf;
;                     const LAS unsigned char* vrow = VT + bi * 20480 + (32 * mt + n) * 160;
;                     const u32x2 lo = *(const LAS u32x2*)(vrow + (kb ^ xr) * 2), hi = *(const LAS u32x2*)(vrow + ((kb + 8) ^ xr) * 2);
;                     const u32x4 t = {lo.x, lo.y, hi.x, hi.y};
;                     Vf[mt * 2 + s2] = __builtin_bit_cast(bf16x8, t);
;     ...
;             if (__ballot(alpha != 1.0f) != 0ull) {
; #pragma unroll
;                 for (int mt = 0; mt < 4; ++mt)
; #pragma unroll
;                     for (int v = 0; v < 16; ++v) O[mt][v] *= alpha;
;             }
;             bf16x8 Pb[2];
; #pragma unroll
;             for (int s2 = 0; s2 < 2; ++s2) {
;                 const u32x4 t = {pg8::cvt_pk_bf16(acc[8 * s2 + 0], acc[8 * s2 + 1]), pg8::cvt_pk_bf16(acc[8 * s2 + 2], acc[8 * s2 + 3]), pg8::cvt_pk_bf16(acc[8 * s2 + 4], acc[8 * s2 + 5]), pg8::cvt_pk_bf16(acc[8 * s2 + 6], acc[8 * s2 + 7])};
;                 Pb[s2] = __builtin_bit_cast(bf16x8, t);
;             }
; #pragma unroll
;             for (int mt = 0; mt < 4; ++mt)
; #pragma unroll
;                 for (int s2 = 0; s2 < 2; ++s2) O[mt] = __builtin_amdgcn_mfma_f32_32x32x16_bf16(Vf[mt * 2 + s2], Pb[s2], O[mt], 0, 0, 0);
	v_pk_mul_f32 v[62:63], v[62:63], v[64:65] op_sel_hi:[1,0]
	v_pk_mul_f32 v[60:61], v[60:61], v[64:65] op_sel_hi:[1,0]
	v_pk_mul_f32 v[58:59], v[58:59], v[64:65] op_sel_hi:[1,0]
	v_pk_mul_f32 v[56:57], v[56:57], v[64:65] op_sel_hi:[1,0]
	v_pk_mul_f32 v[54:55], v[54:55], v[64:65] op_sel_hi:[1,0]
	v_pk_mul_f32 v[52:53], v[52:53], v[64:65] op_sel_hi:[1,0]
	v_pk_mul_f32 v[50:51], v[50:51], v[64:65] op_sel_hi:[1,0]
	v_pk_mul_f32 v[48:49], v[48:49], v[64:65] op_sel_hi:[1,0]
	v_pk_mul_f32 v[46:47], v[46:47], v[64:65] op_sel_hi:[1,0]
	v_pk_mul_f32 v[44:45], v[44:45], v[64:65] op_sel_hi:[1,0]
	v_pk_mul_f32 v[42:43], v[42:43], v[64:65] op_sel_hi:[1,0]
	v_pk_mul_f32 v[40:41], v[40:41], v[64:65] op_sel_hi:[1,0]
	v_pk_mul_f32 v[38:39], v[38:39], v[64:65] op_sel_hi:[1,0]
	v_pk_mul_f32 v[36:37], v[36:37], v[64:65] op_sel_hi:[1,0]
	v_pk_mul_f32 v[34:35], v[34:35], v[64:65] op_sel_hi:[1,0]
	v_pk_mul_f32 v[32:33], v[32:33], v[64:65] op_sel_hi:[1,0]
	v_pk_mul_f32 v[30:31], v[30:31], v[64:65] op_sel_hi:[1,0]
	v_pk_mul_f32 v[28:29], v[28:29], v[64:65] op_sel_hi:[1,0]
	v_pk_mul_f32 v[26:27], v[26:27], v[64:65] op_sel_hi:[1,0]
	v_pk_mul_f32 v[24:25], v[24:25], v[64:65] op_sel_hi:[1,0]
	v_pk_mul_f32 v[22:23], v[22:23], v[64:65] op_sel_hi:[1,0]
	v_pk_mul_f32 v[20:21], v[20:21], v[64:65] op_sel_hi:[1,0]
	v_pk_mul_f32 v[18:19], v[18:19], v[64:65] op_sel_hi:[1,0]
	v_pk_mul_f32 v[16:17], v[16:17], v[64:65] op_sel_hi:[1,0]
	v_pk_mul_f32 v[14:15], v[14:15], v[64:65] op_sel_hi:[1,0]
	v_pk_mul_f32 v[12:13], v[12:13], v[64:65] op_sel_hi:[1,0]
	v_pk_mul_f32 v[10:11], v[10:11], v[64:65] op_sel_hi:[1,0]
	v_pk_mul_f32 v[8:9], v[8:9], v[64:65] op_sel_hi:[1,0]
	v_pk_mul_f32 v[6:7], v[6:7], v[64:65] op_sel_hi:[1,0]
	v_pk_mul_f32 v[4:5], v[4:5], v[64:65] op_sel_hi:[1,0]
	v_pk_mul_f32 v[2:3], v[2:3], v[64:65] op_sel_hi:[1,0]
	v_pk_mul_f32 v[0:1], v[0:1], v[64:65] op_sel_hi:[1,0]
.LBB0_1445:
	v_cvt_pk_bf16_f32 v230, v66, v68
	v_cvt_pk_bf16_f32 v231, v69, v71
	v_cvt_pk_bf16_f32 v232, v72, v77
	v_cvt_pk_bf16_f32 v233, v78, v223
	v_cvt_pk_bf16_f32 v66, v65, v67
	v_cvt_pk_bf16_f32 v67, v70, v73
	v_cvt_pk_bf16_f32 v68, v74, v79
	v_cvt_pk_bf16_f32 v69, v227, v228
	s_waitcnt lgkmcnt(0)
	v_add_f32_e32 v65, v76, v239
	v_mfma_f32_32x32x16_bf16 v[48:63], v[132:135], v[230:233], v[48:63]
	v_fmac_f32_e32 v65, v192, v64
	v_mov_b32_e32 v192, v65
	v_mfma_f32_32x32x16_bf16 v[32:47], v[140:143], v[230:233], v[32:47]
	v_mfma_f32_32x32x16_bf16 v[16:31], v[152:155], v[230:233], v[16:31]
	v_mfma_f32_32x32x16_bf16 v[0:15], v[156:159], v[230:233], v[0:15]
	v_mfma_f32_32x32x16_bf16 v[48:63], v[128:131], v[66:69], v[48:63]
	v_mfma_f32_32x32x16_bf16 v[32:47], v[136:139], v[66:69], v[32:47]
	v_mfma_f32_32x32x16_bf16 v[16:31], v[148:151], v[66:69], v[16:31]
	v_mfma_f32_32x32x16_bf16 v[0:15], v[144:147], v[66:69], v[0:15]
	v_cmp_ne_u32_e32 vcc, 0, v175
	s_cbranch_vccz .LBB0_1450
.LBB0_1446:
	ds_read_b128 v[64:67], v226 offset:8704
	ds_read_b128 v[128:131], v226 offset:8736
	ds_read_b128 v[132:135], v226 offset:8768
	ds_read_b128 v[136:139], v226 offset:8800
	ds_read_b128 v[140:143], v226 offset:8832
	ds_read_b128 v[144:147], v226 offset:8864
	ds_read_b128 v[156:159], v226 offset:8896
	ds_read_b128 v[226:229], v226 offset:8928
	s_waitcnt lgkmcnt(7)
	v_mfma_f32_32x32x16_bf16 v[64:79], v[64:67], v[104:107], 0
	v_add_u32_e32 v149, v224, v216
	s_waitcnt lgkmcnt(6)
	v_mfma_f32_32x32x16_bf16 v[64:79], v[128:131], v[80:83], v[64:79]
	v_add_u32_e32 v128, v224, v206
	v_add_u32_e32 v129, v224, v207
	v_add_u32_e32 v130, v224, v208
	v_add_u32_e32 v131, v224, v209
	s_waitcnt lgkmcnt(5)
	v_mfma_f32_32x32x16_bf16 v[64:79], v[132:135], v[84:87], v[64:79]
	ds_read_b64 v[132:133], v128
	ds_read_b64 v[134:135], v129
	ds_read_b64 v[128:129], v130
	ds_read_b64 v[130:131], v131
	s_waitcnt lgkmcnt(8)
	v_mfma_f32_32x32x16_bf16 v[64:79], v[136:139], v[88:91], v[64:79]
	v_add_u32_e32 v136, v225, v210
	v_add_u32_e32 v137, v136, v211
	v_add_u32_e32 v138, v136, v212
	v_add_u32_e32 v139, v136, v213
	v_add_u32_e32 v148, v136, v214
	s_waitcnt lgkmcnt(7)
	v_mfma_f32_32x32x16_bf16 v[64:79], v[140:143], v[92:95], v[64:79]
	ds_read_b64 v[140:141], v137
	ds_read_b64 v[142:143], v138
	ds_read_b64 v[136:137], v139
	ds_read_b64 v[138:139], v148
	v_add_u32_e32 v148, v224, v215
	s_waitcnt lgkmcnt(10)
	v_mfma_f32_32x32x16_bf16 v[64:79], v[144:147], v[96:99], v[64:79]
	v_add_u32_e32 v144, v224, v217
	v_add_u32_e32 v145, v224, v218
	ds_read_b64 v[152:153], v148 offset:10240
	ds_read_b64 v[154:155], v149 offset:10240
	ds_read_b64 v[148:149], v144 offset:10240
	ds_read_b64 v[150:151], v145 offset:10240
	v_add_u32_e32 v144, v224, v219
	v_add_u32_e32 v145, v224, v220
	v_add_u32_e32 v146, v224, v221
	v_add_u32_e32 v147, v224, v222
	s_waitcnt lgkmcnt(13)
	v_mfma_f32_32x32x16_bf16 v[64:79], v[156:159], v[100:103], v[64:79]
	ds_read_b64 v[156:157], v144 offset:15360
	ds_read_b64 v[158:159], v145 offset:15360
	ds_read_b64 v[144:145], v146 offset:15360
	ds_read_b64 v[146:147], v147 offset:15360
	s_waitcnt lgkmcnt(14)
; __device__ __forceinline__ float lane_get(float v, int src_lane) { return __builtin_bit_cast(float, __builtin_amdgcn_ds_bpermute(src_lane << 2, __builtin_bit_cast(int, v))); }
; __device__ __forceinline__ void dsa_attn_unit(const Ctx& c, int l, int b, int kvh, int qb64) {
;     ...
;             const unsigned wsh = mwd >> (4 * hf);
;             float mx = -INFINITY;
; #pragma unroll
;             for (int v = 0; v < 16; ++v) { const bool selv = (wsh >> ((v & 3) + 8 * (v >> 2))) & 1u; acc[v] = selv ? acc[v] * 0.12751743f : -INFINITY; mx = fmaxf(mx, acc[v]); }
;             mx = fmaxf(mx, lane_get(mx, lane ^ 32));
;             const float m_new = fmaxf(m_run, mx);
;             const float alpha = __builtin_amdgcn_exp2f(m_run - m_new);
;             float rs = 0.f;
; #pragma unroll
;             for (int v = 0; v < 16; ++v) { acc[v] = __builtin_amdgcn_exp2f(acc[v] - m_new); rs += acc[v]; }
;             rs += lane_get(rs, lane ^ 32);
;             l_run = l_run * alpha + rs; m_run = m_new;
;             if (__ballot(alpha != 1.0f) != 0ull) {
; #pragma unroll
;                 for (int mt = 0; mt < 4; ++mt)
; #pragma unroll
;                     for (int v = 0; v < 16; ++v) O[mt][v] *= alpha;
	v_mfma_f32_32x32x16_bf16 v[64:79], v[226:229], v[108:111], v[64:79]
	v_lshrrev_b32_e32 v175, v168, v175
	v_and_b32_e32 v223, 1, v175
	s_nop 9
	v_mul_f32_e32 v64, 0x3e0293ee, v64
	v_cmp_eq_u32_e32 vcc, 1, v223
	v_and_b32_e32 v223, 2, v175
	v_mul_f32_e32 v65, 0x3e0293ee, v65
	v_cndmask_b32_e32 v64, v180, v64, vcc
	v_cmp_ne_u32_e32 vcc, 0, v223
	v_and_b32_e32 v224, 4, v175
	v_mul_f32_e32 v66, 0x3e0293ee, v66
	v_cndmask_b32_e32 v65, v180, v65, vcc
	v_cmp_ne_u32_e32 vcc, 0, v224
	v_max3_f32 v223, v64, s82, v65
	v_mul_f32_e32 v68, 0x3e0293ee, v68
	v_cndmask_b32_e32 v224, v180, v66, vcc
	v_mul_f32_e32 v66, 0x3e0293ee, v67
	v_and_b32_e32 v67, 8, v175
	v_cmp_ne_u32_e32 vcc, 0, v67
	s_nop 1
	v_cndmask_b32_e32 v67, v180, v66, vcc
	v_max3_f32 v66, v223, v224, v67
	v_and_b32_e32 v223, 0x100, v175
	v_cmp_ne_u32_e32 vcc, 0, v223
	s_nop 1
	v_cndmask_b32_e32 v225, v180, v68, vcc
	v_mul_f32_e32 v68, 0x3e0293ee, v69
	v_and_b32_e32 v69, 0x200, v175
	v_cmp_ne_u32_e32 vcc, 0, v69
	v_and_b32_e32 v69, 0x400, v175
	s_nop 0
	v_cndmask_b32_e32 v226, v180, v68, vcc
	v_mul_f32_e32 v68, 0x3e0293ee, v70
	v_cmp_ne_u32_e32 vcc, 0, v69
	v_and_b32_e32 v69, 0x800, v175
	v_max3_f32 v66, v66, v225, v226
	v_cndmask_b32_e32 v70, v180, v68, vcc
	v_mul_f32_e32 v68, 0x3e0293ee, v71
	v_cmp_ne_u32_e32 vcc, 0, v69
	v_and_b32_e32 v69, 0x10000, v175
	s_nop 0
	v_cndmask_b32_e32 v227, v180, v68, vcc
	v_mul_f32_e32 v68, 0x3e0293ee, v72
	v_cmp_ne_u32_e32 vcc, 0, v69
	v_and_b32_e32 v69, 0x20000, v175
	v_max3_f32 v66, v66, v70, v227
	v_cndmask_b32_e32 v228, v180, v68, vcc
	v_mul_f32_e32 v68, 0x3e0293ee, v73
	v_cmp_ne_u32_e32 vcc, 0, v69
	v_and_b32_e32 v69, 0x40000, v175
	s_nop 0
	v_cndmask_b32_e32 v73, v180, v68, vcc
	v_mul_f32_e32 v68, 0x3e0293ee, v74
	v_cmp_ne_u32_e32 vcc, 0, v69
	v_and_b32_e32 v69, 0x80000, v175
	v_max3_f32 v66, v66, v228, v73
	v_cndmask_b32_e32 v74, v180, v68, vcc
	v_mul_f32_e32 v68, 0x3e0293ee, v75
	v_cmp_ne_u32_e32 vcc, 0, v69
	v_and_b32_e32 v69, 0x1000000, v175
	s_nop 0
	v_cndmask_b32_e32 v75, v180, v68, vcc
	v_mul_f32_e32 v68, 0x3e0293ee, v76
	v_cmp_ne_u32_e32 vcc, 0, v69
	v_and_b32_e32 v69, 0x2000000, v175
	v_max3_f32 v66, v66, v74, v75
	v_cndmask_b32_e32 v76, v180, v68, vcc
	v_mul_f32_e32 v68, 0x3e0293ee, v77
	v_cmp_ne_u32_e32 vcc, 0, v69
	v_and_b32_e32 v69, 0x4000000, v175
	s_nop 0
	v_cndmask_b32_e32 v229, v180, v68, vcc
	v_mul_f32_e32 v68, 0x3e0293ee, v78
	v_cmp_ne_u32_e32 vcc, 0, v69
	v_and_b32_e32 v69, 0x8000000, v175
	v_max3_f32 v66, v66, v76, v229
	v_cndmask_b32_e32 v230, v180, v68, vcc
	v_mul_f32_e32 v68, 0x3e0293ee, v79
	v_cmp_ne_u32_e32 vcc, 0, v69
	s_nop 1
	v_cndmask_b32_e32 v231, v180, v68, vcc
	v_max3_f32 v66, v66, v230, v231
	v_mov_b32_e32 v68, v66
	v_mov_b32_e32 v238, v66
	s_nop 1
	v_permlane32_swap_b32_e32 v68, v238
	s_waitcnt lgkmcnt(0)
	v_max3_f32 v223, v174, v68, v238
	v_sub_f32_e32 v64, v64, v223
	v_exp_f32_e32 v66, v64
	v_sub_f32_e32 v65, v65, v223
	v_exp_f32_e32 v68, v65
	v_sub_f32_e32 v65, v224, v223
	v_exp_f32_e32 v69, v65
	v_sub_f32_e32 v65, v67, v223
	v_exp_f32_e32 v71, v65
	v_sub_f32_e32 v65, v225, v223
	v_add_f32_e32 v77, 0, v66
	v_exp_f32_e32 v72, v65
	v_add_f32_e32 v65, v68, v77
	v_add_f32_e32 v65, v69, v65
	v_add_f32_e32 v65, v71, v65
	v_add_f32_e32 v67, v72, v65
	v_sub_f32_e32 v65, v226, v223
	v_exp_f32_e32 v77, v65
	v_sub_f32_e32 v65, v70, v223
	v_exp_f32_e32 v78, v65
	v_sub_f32_e32 v65, v227, v223
	v_sub_f32_e32 v64, v174, v223
	v_exp_f32_e32 v174, v65
	v_sub_f32_e32 v65, v228, v223
	v_exp_f32_e32 v65, v65
	v_add_f32_e32 v67, v77, v67
	v_add_f32_e32 v67, v78, v67
	v_add_f32_e32 v67, v174, v67
	v_add_f32_e32 v79, v65, v67
	v_sub_f32_e32 v67, v73, v223
	v_exp_f32_e32 v67, v67
	v_sub_f32_e32 v70, v74, v223
	v_exp_f32_e32 v70, v70
	v_sub_f32_e32 v73, v75, v223
	v_exp_f32_e32 v73, v73
	v_sub_f32_e32 v74, v76, v223
	v_exp_f32_e32 v74, v74
	v_sub_f32_e32 v76, v229, v223
	v_add_f32_e32 v75, v67, v79
	v_exp_f32_e32 v79, v76
	v_sub_f32_e32 v76, v230, v223
	v_add_f32_e32 v75, v70, v75
	v_exp_f32_e32 v175, v76
	v_sub_f32_e32 v76, v231, v223
	v_add_f32_e32 v75, v73, v75
	v_exp_f32_e32 v224, v76
	v_add_f32_e32 v75, v74, v75
	v_add_f32_e32 v75, v79, v75
	v_add_f32_e32 v75, v175, v75
	v_add_f32_e32 v75, v224, v75
	v_exp_f32_e32 v64, v64
	v_mov_b32_e32 v76, v75
	v_mov_b32_e32 v239, v75
	s_nop 1
	v_permlane32_swap_b32_e32 v76, v239
	v_cmp_neq_f32_e32 vcc, 1.0, v64
	s_cbranch_vccz .LBB0_1448
	v_pk_mul_f32 v[62:63], v[62:63], v[64:65] op_sel_hi:[1,0]
	v_pk_mul_f32 v[60:61], v[60:61], v[64:65] op_sel_hi:[1,0]
	v_pk_mul_f32 v[58:59], v[58:59], v[64:65] op_sel_hi:[1,0]
	v_pk_mul_f32 v[56:57], v[56:57], v[64:65] op_sel_hi:[1,0]
	v_pk_mul_f32 v[54:55], v[54:55], v[64:65] op_sel_hi:[1,0]
	v_pk_mul_f32 v[52:53], v[52:53], v[64:65] op_sel_hi:[1,0]
	v_pk_mul_f32 v[50:51], v[50:51], v[64:65] op_sel_hi:[1,0]
	v_pk_mul_f32 v[48:49], v[48:49], v[64:65] op_sel_hi:[1,0]
	v_pk_mul_f32 v[46:47], v[46:47], v[64:65] op_sel_hi:[1,0]
	v_pk_mul_f32 v[44:45], v[44:45], v[64:65] op_sel_hi:[1,0]
	v_pk_mul_f32 v[42:43], v[42:43], v[64:65] op_sel_hi:[1,0]
	v_pk_mul_f32 v[40:41], v[40:41], v[64:65] op_sel_hi:[1,0]
	v_pk_mul_f32 v[38:39], v[38:39], v[64:65] op_sel_hi:[1,0]
	v_pk_mul_f32 v[36:37], v[36:37], v[64:65] op_sel_hi:[1,0]
	v_pk_mul_f32 v[34:35], v[34:35], v[64:65] op_sel_hi:[1,0]
	v_pk_mul_f32 v[32:33], v[32:33], v[64:65] op_sel_hi:[1,0]
	v_pk_mul_f32 v[30:31], v[30:31], v[64:65] op_sel_hi:[1,0]
	v_pk_mul_f32 v[28:29], v[28:29], v[64:65] op_sel_hi:[1,0]
	v_pk_mul_f32 v[26:27], v[26:27], v[64:65] op_sel_hi:[1,0]
	v_pk_mul_f32 v[24:25], v[24:25], v[64:65] op_sel_hi:[1,0]
	v_pk_mul_f32 v[22:23], v[22:23], v[64:65] op_sel_hi:[1,0]
	v_pk_mul_f32 v[20:21], v[20:21], v[64:65] op_sel_hi:[1,0]
	v_pk_mul_f32 v[18:19], v[18:19], v[64:65] op_sel_hi:[1,0]
	v_pk_mul_f32 v[16:17], v[16:17], v[64:65] op_sel_hi:[1,0]
	v_pk_mul_f32 v[14:15], v[14:15], v[64:65] op_sel_hi:[1,0]
	v_pk_mul_f32 v[12:13], v[12:13], v[64:65] op_sel_hi:[1,0]
	v_pk_mul_f32 v[10:11], v[10:11], v[64:65] op_sel_hi:[1,0]
	v_pk_mul_f32 v[8:9], v[8:9], v[64:65] op_sel_hi:[1,0]
	v_pk_mul_f32 v[6:7], v[6:7], v[64:65] op_sel_hi:[1,0]
	v_pk_mul_f32 v[4:5], v[4:5], v[64:65] op_sel_hi:[1,0]
	v_pk_mul_f32 v[2:3], v[2:3], v[64:65] op_sel_hi:[1,0]
	v_pk_mul_f32 v[0:1], v[0:1], v[64:65] op_sel_hi:[1,0]
; __device__ __forceinline__ unsigned cvt_pk_bf16(float lo, float hi) { unsigned r; asm volatile("v_cvt_pk_bf16_f32 %0, %1, %2" : "=v"(r) : "v"(lo), "v"(hi)); return r; }
; __device__ __forceinline__ void dsa_attn_unit(const Ctx& c, int l, int b, int kvh, int qb64) {
;     ...
;             bf16x8 Pb[2];
; #pragma unroll
;             for (int s2 = 0; s2 < 2; ++s2) {
;                 const u32x4 t = {pg8::cvt_pk_bf16(acc[8 * s2 + 0], acc[8 * s2 + 1]), pg8::cvt_pk_bf16(acc[8 * s2 + 2], acc[8 * s2 + 3]), pg8::cvt_pk_bf16(acc[8 * s2 + 4], acc[8 * s2 + 5]), pg8::cvt_pk_bf16(acc[8 * s2 + 6], acc[8 * s2 + 7])};
;                 Pb[s2] = __builtin_bit_cast(bf16x8, t);
;             }
; #pragma unroll
;             for (int mt = 0; mt < 4; ++mt)
; #pragma unroll
;                 for (int s2 = 0; s2 < 2; ++s2) O[mt] = __builtin_amdgcn_mfma_f32_32x32x16_bf16(Vf[mt * 2 + s2], Pb[s2], O[mt], 0, 0, 0);
;         }
.LBB0_1448:
	v_cvt_pk_bf16_f32 v226, v66, v68
	v_cvt_pk_bf16_f32 v227, v69, v71
	v_cvt_pk_bf16_f32 v228, v72, v77
	v_cvt_pk_bf16_f32 v229, v78, v174
	v_cvt_pk_bf16_f32 v66, v65, v67
	v_cvt_pk_bf16_f32 v67, v70, v73
	v_cvt_pk_bf16_f32 v68, v74, v79
	v_cvt_pk_bf16_f32 v69, v175, v224
	s_waitcnt lgkmcnt(0)
	v_add_f32_e32 v65, v76, v239
	v_mfma_f32_32x32x16_bf16 v[48:63], v[132:135], v[226:229], v[48:63]
	v_fmac_f32_e32 v65, v192, v64
	v_mov_b32_e32 v192, v65
	v_mfma_f32_32x32x16_bf16 v[32:47], v[140:143], v[226:229], v[32:47]
	v_mfma_f32_32x32x16_bf16 v[16:31], v[152:155], v[226:229], v[16:31]
	v_mfma_f32_32x32x16_bf16 v[0:15], v[156:159], v[226:229], v[0:15]
	v_mfma_f32_32x32x16_bf16 v[48:63], v[128:131], v[66:69], v[48:63]
	v_mfma_f32_32x32x16_bf16 v[32:47], v[136:139], v[66:69], v[32:47]
	v_mfma_f32_32x32x16_bf16 v[16:31], v[148:151], v[66:69], v[16:31]
	v_mfma_f32_32x32x16_bf16 v[0:15], v[144:147], v[66:69], v[0:15]
	s_and_b64 vcc, exec, s[4:5]
	s_cbranch_vccz .LBB0_1439
	s_branch .LBB0_1438

; #define LAS __attribute__((address_space(3)))
; __device__ __forceinline__ void dsa_attn_unit(const Ctx& c, int l, int b, int kvh, int qb64) {
;     ...
;         for (int sub = 0; sub < 2; ++sub) {
;             const unsigned mwd = mw[sub];
;             if (__ballot(mwd != 0u) == 0ull) continue;
;             f32x16 acc;
; #pragma unroll
;             for (int v = 0; v < 16; ++v) acc[v] = 0.f;
;             const LAS unsigned char* kp = Kt + bi * 17408 + (sub * 32 + n) * 272 + hf * 16;
;             bf16x8 Kf[8];
; #pragma unroll
;             for (int ks = 0; ks < 8; ++ks) Kf[ks] = *(const LAS bf16x8*)(kp + ks * 32);
;             __builtin_amdgcn_sched_barrier(0);
; #pragma unroll
;             for (int ks = 0; ks < 8; ++ks) acc = __builtin_amdgcn_mfma_f32_32x32x16_bf16(Kf[ks], Qf[ks], acc, 0, 0, 0);
;             bf16x8 Vf[8];
; #pragma unroll
;             for (int mt = 0; mt < 4; ++mt)
; #pragma unroll
;                 for (int s2 = 0; s2 < 2; ++s2) {
;                     const int xr = 4 * (4 * mt + (n >> 3)), kb = sub * 32 + 16 * s2 + 4 * hf;
;                     const LAS unsigned char* vrow = VT + bi * 20480 + (32 * mt + n) * 160;
;                     const u32x2 lo = *(const LAS u32x2*)(vrow + (kb ^ xr) * 2), hi = *(const LAS u32x2*)(vrow + ((kb + 8) ^ xr) * 2);
;                     const u32x4 t = {lo.x, lo.y, hi.x, hi.y};
;                     Vf[mt * 2 + s2] = __builtin_bit_cast(bf16x8, t);
;                 }
;             __builtin_amdgcn_sched_barrier(0);
;             const unsigned wsh = mwd >> (4 * hf);
;             float mx = -INFINITY;
; #pragma unroll
;             for (int v = 0; v < 16; ++v) { const bool selv = (wsh >> ((v & 3) + 8 * (v >> 2))) & 1u; acc[v] = selv ? acc[v] * 0.12751743f : -INFINITY; mx = fmaxf(mx, acc[v]); }
;             mx = fmaxf(mx, lane_get(mx, lane ^ 32));
;             const float m_new = fmaxf(m_run, mx);
;             const float alpha = __builtin_amdgcn_exp2f(m_run - m_new);
;             float rs = 0.f;
; #pragma unroll
;             for (int v = 0; v < 16; ++v) { acc[v] = __builtin_amdgcn_exp2f(acc[v] - m_new); rs += acc[v]; }
;             rs += lane_get(rs, lane ^ 32);
;             l_run = l_run * alpha + rs; m_run = m_new;
;             if (__ballot(alpha != 1.0f) != 0ull) {
.LBB0_2892:
	s_and_b32 s11, s9, 1
	s_mul_i32 s16, s11, 0x4400
	s_mul_i32 s30, s11, 0x5000
	v_add_u32_e32 v64, s16, v185
	v_add_u32_e32 v225, s30, v163
	v_add_u32_e32 v226, v64, v187
	v_add_u32_e32 v224, v225, v188
	v_cmp_ne_u32_e32 vcc, 0, v174
	s_cbranch_vccz .LBB0_2899
	ds_read_b128 v[64:67], v226
	ds_read_b128 v[128:131], v226 offset:32
	ds_read_b128 v[132:135], v226 offset:64
	ds_read_b128 v[136:139], v226 offset:96
	ds_read_b128 v[140:143], v226 offset:128
	ds_read_b128 v[144:147], v226 offset:160
	ds_read_b128 v[156:159], v226 offset:192
	ds_read_b128 v[228:231], v226 offset:224
	s_waitcnt lgkmcnt(7)
	v_mfma_f32_32x32x16_bf16 v[64:79], v[64:67], v[104:107], 0
	v_add_u32_e32 v148, v224, v197
	v_add_u32_e32 v149, v224, v198
	s_waitcnt lgkmcnt(6)
	v_mfma_f32_32x32x16_bf16 v[64:79], v[128:131], v[80:83], v[64:79]
	v_add_u32_e32 v128, v224, v189
	v_add_u32_e32 v129, v224, v190
	v_add_u32_e32 v130, v224, v191
	v_add_u32_e32 v131, v224, v192
	s_waitcnt lgkmcnt(5)
	v_mfma_f32_32x32x16_bf16 v[64:79], v[132:135], v[84:87], v[64:79]
	ds_read_b64 v[132:133], v128
	ds_read_b64 v[134:135], v129
	ds_read_b64 v[128:129], v130
	ds_read_b64 v[130:131], v131
	s_waitcnt lgkmcnt(8)
	v_mfma_f32_32x32x16_bf16 v[64:79], v[136:139], v[88:91], v[64:79]
	v_add_u32_e32 v136, v224, v193
	v_add_u32_e32 v137, v224, v194
	v_add_u32_e32 v138, v224, v195
	v_add_u32_e32 v139, v224, v196
	s_waitcnt lgkmcnt(7)
	v_mfma_f32_32x32x16_bf16 v[64:79], v[140:143], v[92:95], v[64:79]
	ds_read_b64 v[140:141], v136 offset:5120
	ds_read_b64 v[142:143], v137 offset:5120
	ds_read_b64 v[136:137], v138 offset:5120
	ds_read_b64 v[138:139], v139 offset:5120
	s_waitcnt lgkmcnt(10)
	v_mfma_f32_32x32x16_bf16 v[64:79], v[144:147], v[96:99], v[64:79]
	v_add_u32_e32 v144, v224, v199
	v_add_u32_e32 v145, v224, v200
	ds_read_b64 v[152:153], v148 offset:10240
	ds_read_b64 v[154:155], v149 offset:10240
	ds_read_b64 v[148:149], v144 offset:10240
	ds_read_b64 v[150:151], v145 offset:10240
	v_add_u32_e32 v144, v224, v201
	v_add_u32_e32 v145, v224, v202
	v_add_u32_e32 v146, v224, v203
	v_add_u32_e32 v147, v224, v204
	s_waitcnt lgkmcnt(13)
	v_mfma_f32_32x32x16_bf16 v[64:79], v[156:159], v[100:103], v[64:79]
	ds_read_b64 v[156:157], v144 offset:15360
	ds_read_b64 v[158:159], v145 offset:15360
	ds_read_b64 v[144:145], v146 offset:15360
	ds_read_b64 v[146:147], v147 offset:15360
	s_waitcnt lgkmcnt(14)
	v_mfma_f32_32x32x16_bf16 v[64:79], v[228:231], v[108:111], v[64:79]
	v_lshrrev_b32_e32 v174, v168, v174
	v_and_b32_e32 v227, 1, v174
	s_nop 9
	v_mul_f32_e32 v64, 0x3e0293ee, v64
	v_cmp_eq_u32_e32 vcc, 1, v227
	v_and_b32_e32 v227, 2, v174
	v_mul_f32_e32 v65, 0x3e0293ee, v65
	v_cndmask_b32_e32 v64, v180, v64, vcc
	v_cmp_ne_u32_e32 vcc, 0, v227
	v_and_b32_e32 v228, 4, v174
	v_mul_f32_e32 v66, 0x3e0293ee, v66
	v_cndmask_b32_e32 v65, v180, v65, vcc
	v_cmp_ne_u32_e32 vcc, 0, v228
	v_max3_f32 v227, v64, s60, v65
	v_mul_f32_e32 v68, 0x3e0293ee, v68
	v_cndmask_b32_e32 v228, v180, v66, vcc
	v_mul_f32_e32 v66, 0x3e0293ee, v67
	v_and_b32_e32 v67, 8, v174
	v_cmp_ne_u32_e32 vcc, 0, v67
	s_nop 1
	v_cndmask_b32_e32 v67, v180, v66, vcc
	v_max3_f32 v66, v227, v228, v67
	v_and_b32_e32 v227, 0x100, v174
	v_cmp_ne_u32_e32 vcc, 0, v227
	s_nop 1
	v_cndmask_b32_e32 v227, v180, v68, vcc
	v_mul_f32_e32 v68, 0x3e0293ee, v69
	v_and_b32_e32 v69, 0x200, v174
	v_cmp_ne_u32_e32 vcc, 0, v69
	v_and_b32_e32 v69, 0x400, v174
	s_nop 0
	v_cndmask_b32_e32 v229, v180, v68, vcc
	v_mul_f32_e32 v68, 0x3e0293ee, v70
	v_cmp_ne_u32_e32 vcc, 0, v69
	v_and_b32_e32 v69, 0x800, v174
	v_max3_f32 v66, v66, v227, v229
	v_cndmask_b32_e32 v70, v180, v68, vcc
	v_mul_f32_e32 v68, 0x3e0293ee, v71
	v_cmp_ne_u32_e32 vcc, 0, v69
	v_and_b32_e32 v69, 0x10000, v174
	s_nop 0
	v_cndmask_b32_e32 v230, v180, v68, vcc
	v_mul_f32_e32 v68, 0x3e0293ee, v72
	v_cmp_ne_u32_e32 vcc, 0, v69
	v_and_b32_e32 v69, 0x20000, v174
	v_max3_f32 v66, v66, v70, v230
	v_cndmask_b32_e32 v231, v180, v68, vcc
	v_mul_f32_e32 v68, 0x3e0293ee, v73
	v_cmp_ne_u32_e32 vcc, 0, v69
	v_and_b32_e32 v69, 0x40000, v174
	s_nop 0
	v_cndmask_b32_e32 v73, v180, v68, vcc
	v_mul_f32_e32 v68, 0x3e0293ee, v74
	v_cmp_ne_u32_e32 vcc, 0, v69
	v_and_b32_e32 v69, 0x80000, v174
	v_max3_f32 v66, v66, v231, v73
	v_cndmask_b32_e32 v74, v180, v68, vcc
	v_mul_f32_e32 v68, 0x3e0293ee, v75
	v_cmp_ne_u32_e32 vcc, 0, v69
	v_and_b32_e32 v69, 0x1000000, v174
	s_nop 0
	v_cndmask_b32_e32 v75, v180, v68, vcc
	v_mul_f32_e32 v68, 0x3e0293ee, v76
	v_cmp_ne_u32_e32 vcc, 0, v69
	v_and_b32_e32 v69, 0x2000000, v174
	v_max3_f32 v66, v66, v74, v75
	v_cndmask_b32_e32 v76, v180, v68, vcc
	v_mul_f32_e32 v68, 0x3e0293ee, v77
	v_cmp_ne_u32_e32 vcc, 0, v69
	v_and_b32_e32 v69, 0x4000000, v174
	s_nop 0
	v_cndmask_b32_e32 v232, v180, v68, vcc
	v_mul_f32_e32 v68, 0x3e0293ee, v78
	v_cmp_ne_u32_e32 vcc, 0, v69
	v_and_b32_e32 v69, 0x8000000, v174
	v_max3_f32 v66, v66, v76, v232
	v_cndmask_b32_e32 v233, v180, v68, vcc
	v_mul_f32_e32 v68, 0x3e0293ee, v79
	v_cmp_ne_u32_e32 vcc, 0, v69
	s_nop 1
	v_cndmask_b32_e32 v234, v180, v68, vcc
	v_max3_f32 v66, v66, v233, v234
	v_mov_b32_e32 v68, v66
	v_mov_b32_e32 v238, v66
	s_nop 1
	v_permlane32_swap_b32_e32 v68, v238
	s_waitcnt lgkmcnt(0)
	v_max3_f32 v174, v223, v68, v238
	v_sub_f32_e32 v64, v64, v174
	v_exp_f32_e32 v66, v64
	v_sub_f32_e32 v65, v65, v174
	v_exp_f32_e32 v68, v65
	v_sub_f32_e32 v65, v228, v174
	v_exp_f32_e32 v69, v65
	v_sub_f32_e32 v65, v67, v174
	v_exp_f32_e32 v71, v65
	v_sub_f32_e32 v65, v227, v174
	v_add_f32_e32 v77, 0, v66
	v_exp_f32_e32 v72, v65
	v_add_f32_e32 v65, v68, v77
	v_add_f32_e32 v65, v69, v65
	v_add_f32_e32 v65, v71, v65
	v_add_f32_e32 v67, v72, v65
	v_sub_f32_e32 v65, v229, v174
	v_exp_f32_e32 v77, v65
	v_sub_f32_e32 v65, v70, v174
	v_exp_f32_e32 v78, v65
	v_sub_f32_e32 v65, v230, v174
	v_sub_f32_e32 v64, v223, v174
	v_exp_f32_e32 v223, v65
	v_sub_f32_e32 v65, v231, v174
	v_exp_f32_e32 v65, v65
	v_add_f32_e32 v67, v77, v67
	v_add_f32_e32 v67, v78, v67
	v_add_f32_e32 v67, v223, v67
	v_add_f32_e32 v79, v65, v67
	v_sub_f32_e32 v67, v73, v174
	v_exp_f32_e32 v67, v67
	v_sub_f32_e32 v70, v74, v174
	v_exp_f32_e32 v70, v70
	v_sub_f32_e32 v73, v75, v174
	v_exp_f32_e32 v73, v73
	v_sub_f32_e32 v74, v76, v174
	v_exp_f32_e32 v74, v74
	v_sub_f32_e32 v76, v232, v174
	v_add_f32_e32 v75, v67, v79
	v_exp_f32_e32 v79, v76
	v_sub_f32_e32 v76, v233, v174
	v_add_f32_e32 v75, v70, v75
	v_exp_f32_e32 v227, v76
	v_sub_f32_e32 v76, v234, v174
	v_add_f32_e32 v75, v73, v75
	v_exp_f32_e32 v228, v76
	v_add_f32_e32 v75, v74, v75
	v_add_f32_e32 v75, v79, v75
	v_add_f32_e32 v75, v227, v75
	v_add_f32_e32 v75, v228, v75
	v_exp_f32_e32 v64, v64
	v_mov_b32_e32 v76, v75
	v_mov_b32_e32 v239, v75
	s_nop 1
	v_permlane32_swap_b32_e32 v76, v239
	v_cmp_neq_f32_e32 vcc, 1.0, v64
	s_cbranch_vccz .LBB0_2895
; __device__ __forceinline__ unsigned cvt_pk_bf16(float lo, float hi) { unsigned r; asm volatile("v_cvt_pk_bf16_f32 %0, %1, %2" : "=v"(r) : "v"(lo), "v"(hi)); return r; }
; #define LAS __attribute__((address_space(3)))
; __device__ __forceinline__ void dsa_attn_unit(const Ctx& c, int l, int b, int kvh, int qb64) {
;     ...
;             const LAS unsigned char* kp = Kt + bi * 17408 + (sub * 32 + n) * 272 + hf * 16;
;             bf16x8 Kf[8];
; #pragma unroll
;             for (int ks = 0; ks < 8; ++ks) Kf[ks] = *(const LAS bf16x8*)(kp + ks * 32);
;             __builtin_amdgcn_sched_barrier(0);
; #pragma unroll
;             for (int ks = 0; ks < 8; ++ks) acc = __builtin_amdgcn_mfma_f32_32x32x16_bf16(Kf[ks], Qf[ks], acc, 0, 0, 0);
;             bf16x8 Vf[8];
; #pragma unroll
;             for (int mt = 0; mt < 4; ++mt)
; #pragma unroll
;                 for (int s2 = 0; s2 < 2; ++s2) {
;                     const int xr = 4 * (4 * mt + (n >> 3)), kb = sub * 32 + 16 * s2 + 4 * hf;
;                     const LAS unsigned char* vrow = VT + bi * 20480 + (32 * mt + n) * 160;
;                     const u32x2 lo = *(const LAS u32x2*)(vrow + (kb ^ xr) * 2), hi = *(const LAS u32x2*)(vrow + ((kb + 8) ^ xr) * 2);
;                     const u32x4 t = {lo.x, lo.y, hi.x, hi.y};
;                     Vf[mt * 2 + s2] = __builtin_bit_cast(bf16x8, t);
;     ...
;             if (__ballot(alpha != 1.0f) != 0ull) {
; #pragma unroll
;                 for (int mt = 0; mt < 4; ++mt)
; #pragma unroll
;                     for (int v = 0; v < 16; ++v) O[mt][v] *= alpha;
;             }
;             bf16x8 Pb[2];
; #pragma unroll
;             for (int s2 = 0; s2 < 2; ++s2) {
;                 const u32x4 t = {pg8::cvt_pk_bf16(acc[8 * s2 + 0], acc[8 * s2 + 1]), pg8::cvt_pk_bf16(acc[8 * s2 + 2], acc[8 * s2 + 3]), pg8::cvt_pk_bf16(acc[8 * s2 + 4], acc[8 * s2 + 5]), pg8::cvt_pk_bf16(acc[8 * s2 + 6], acc[8 * s2 + 7])};
;                 Pb[s2] = __builtin_bit_cast(bf16x8, t);
;             }
; #pragma unroll
;             for (int mt = 0; mt < 4; ++mt)
; #pragma unroll
;                 for (int s2 = 0; s2 < 2; ++s2) O[mt] = __builtin_amdgcn_mfma_f32_32x32x16_bf16(Vf[mt * 2 + s2], Pb[s2], O[mt], 0, 0, 0);
	v_pk_mul_f32 v[62:63], v[62:63], v[64:65] op_sel_hi:[1,0]
	v_pk_mul_f32 v[60:61], v[60:61], v[64:65] op_sel_hi:[1,0]
	v_pk_mul_f32 v[58:59], v[58:59], v[64:65] op_sel_hi:[1,0]
	v_pk_mul_f32 v[56:57], v[56:57], v[64:65] op_sel_hi:[1,0]
	v_pk_mul_f32 v[54:55], v[54:55], v[64:65] op_sel_hi:[1,0]
	v_pk_mul_f32 v[52:53], v[52:53], v[64:65] op_sel_hi:[1,0]
	v_pk_mul_f32 v[50:51], v[50:51], v[64:65] op_sel_hi:[1,0]
	v_pk_mul_f32 v[48:49], v[48:49], v[64:65] op_sel_hi:[1,0]
	v_pk_mul_f32 v[46:47], v[46:47], v[64:65] op_sel_hi:[1,0]
	v_pk_mul_f32 v[44:45], v[44:45], v[64:65] op_sel_hi:[1,0]
	v_pk_mul_f32 v[42:43], v[42:43], v[64:65] op_sel_hi:[1,0]
	v_pk_mul_f32 v[40:41], v[40:41], v[64:65] op_sel_hi:[1,0]
	v_pk_mul_f32 v[38:39], v[38:39], v[64:65] op_sel_hi:[1,0]
	v_pk_mul_f32 v[36:37], v[36:37], v[64:65] op_sel_hi:[1,0]
	v_pk_mul_f32 v[34:35], v[34:35], v[64:65] op_sel_hi:[1,0]
	v_pk_mul_f32 v[32:33], v[32:33], v[64:65] op_sel_hi:[1,0]
	v_pk_mul_f32 v[30:31], v[30:31], v[64:65] op_sel_hi:[1,0]
	v_pk_mul_f32 v[28:29], v[28:29], v[64:65] op_sel_hi:[1,0]
	v_pk_mul_f32 v[26:27], v[26:27], v[64:65] op_sel_hi:[1,0]
	v_pk_mul_f32 v[24:25], v[24:25], v[64:65] op_sel_hi:[1,0]
	v_pk_mul_f32 v[22:23], v[22:23], v[64:65] op_sel_hi:[1,0]
	v_pk_mul_f32 v[20:21], v[20:21], v[64:65] op_sel_hi:[1,0]
	v_pk_mul_f32 v[18:19], v[18:19], v[64:65] op_sel_hi:[1,0]
	v_pk_mul_f32 v[16:17], v[16:17], v[64:65] op_sel_hi:[1,0]
	v_pk_mul_f32 v[14:15], v[14:15], v[64:65] op_sel_hi:[1,0]
	v_pk_mul_f32 v[12:13], v[12:13], v[64:65] op_sel_hi:[1,0]
	v_pk_mul_f32 v[10:11], v[10:11], v[64:65] op_sel_hi:[1,0]
	v_pk_mul_f32 v[8:9], v[8:9], v[64:65] op_sel_hi:[1,0]
	v_pk_mul_f32 v[6:7], v[6:7], v[64:65] op_sel_hi:[1,0]
	v_pk_mul_f32 v[4:5], v[4:5], v[64:65] op_sel_hi:[1,0]
	v_pk_mul_f32 v[2:3], v[2:3], v[64:65] op_sel_hi:[1,0]
	v_pk_mul_f32 v[0:1], v[0:1], v[64:65] op_sel_hi:[1,0]
.LBB0_2895:
	v_cvt_pk_bf16_f32 v230, v66, v68
	v_cvt_pk_bf16_f32 v231, v69, v71
	v_cvt_pk_bf16_f32 v232, v72, v77
	v_cvt_pk_bf16_f32 v233, v78, v223
	v_cvt_pk_bf16_f32 v66, v65, v67
	v_cvt_pk_bf16_f32 v67, v70, v73
	v_cvt_pk_bf16_f32 v68, v74, v79
	v_cvt_pk_bf16_f32 v69, v227, v228
	s_waitcnt lgkmcnt(0)
	v_add_f32_e32 v65, v76, v239
	v_mfma_f32_32x32x16_bf16 v[48:63], v[132:135], v[230:233], v[48:63]
	v_fmac_f32_e32 v65, v213, v64
	v_mov_b32_e32 v213, v65
	v_mfma_f32_32x32x16_bf16 v[32:47], v[140:143], v[230:233], v[32:47]
	v_mfma_f32_32x32x16_bf16 v[16:31], v[152:155], v[230:233], v[16:31]
	v_mfma_f32_32x32x16_bf16 v[0:15], v[156:159], v[230:233], v[0:15]
	v_mfma_f32_32x32x16_bf16 v[48:63], v[128:131], v[66:69], v[48:63]
	v_mfma_f32_32x32x16_bf16 v[32:47], v[136:139], v[66:69], v[32:47]
	v_mfma_f32_32x32x16_bf16 v[16:31], v[148:151], v[66:69], v[16:31]
	v_mfma_f32_32x32x16_bf16 v[0:15], v[144:147], v[66:69], v[0:15]
	v_cmp_ne_u32_e32 vcc, 0, v175
	s_cbranch_vccz .LBB0_2900
.LBB0_2896:
	ds_read_b128 v[64:67], v226 offset:8704
	ds_read_b128 v[128:131], v226 offset:8736
	ds_read_b128 v[132:135], v226 offset:8768
	ds_read_b128 v[136:139], v226 offset:8800
	ds_read_b128 v[140:143], v226 offset:8832
	ds_read_b128 v[144:147], v226 offset:8864
	ds_read_b128 v[156:159], v226 offset:8896
	ds_read_b128 v[226:229], v226 offset:8928
	s_waitcnt lgkmcnt(7)
	v_mfma_f32_32x32x16_bf16 v[64:79], v[64:67], v[104:107], 0
	v_add_u32_e32 v149, v224, v216
	s_waitcnt lgkmcnt(6)
	v_mfma_f32_32x32x16_bf16 v[64:79], v[128:131], v[80:83], v[64:79]
	v_add_u32_e32 v128, v224, v205
	v_add_u32_e32 v129, v224, v206
	v_add_u32_e32 v130, v224, v207
	v_add_u32_e32 v131, v224, v208
	s_waitcnt lgkmcnt(5)
	v_mfma_f32_32x32x16_bf16 v[64:79], v[132:135], v[84:87], v[64:79]
	ds_read_b64 v[132:133], v128
	ds_read_b64 v[134:135], v129
	ds_read_b64 v[128:129], v130
	ds_read_b64 v[130:131], v131
	s_waitcnt lgkmcnt(8)
	v_mfma_f32_32x32x16_bf16 v[64:79], v[136:139], v[88:91], v[64:79]
	v_add_u32_e32 v136, v225, v209
	v_add_u32_e32 v137, v136, v210
	v_add_u32_e32 v138, v136, v211
	v_add_u32_e32 v139, v136, v212
	v_add_u32_e32 v148, v136, v214
	s_waitcnt lgkmcnt(7)
	v_mfma_f32_32x32x16_bf16 v[64:79], v[140:143], v[92:95], v[64:79]
	ds_read_b64 v[140:141], v137
	ds_read_b64 v[142:143], v138
	ds_read_b64 v[136:137], v139
	ds_read_b64 v[138:139], v148
	v_add_u32_e32 v148, v224, v215
	s_waitcnt lgkmcnt(10)
	v_mfma_f32_32x32x16_bf16 v[64:79], v[144:147], v[96:99], v[64:79]
	v_add_u32_e32 v144, v224, v217
	v_add_u32_e32 v145, v224, v218
	ds_read_b64 v[152:153], v148 offset:10240
	ds_read_b64 v[154:155], v149 offset:10240
	ds_read_b64 v[148:149], v144 offset:10240
	ds_read_b64 v[150:151], v145 offset:10240
	v_add_u32_e32 v144, v224, v219
	v_add_u32_e32 v145, v224, v220
	v_add_u32_e32 v146, v224, v221
	v_add_u32_e32 v147, v224, v222
	s_waitcnt lgkmcnt(13)
	v_mfma_f32_32x32x16_bf16 v[64:79], v[156:159], v[100:103], v[64:79]
	ds_read_b64 v[156:157], v144 offset:15360
	ds_read_b64 v[158:159], v145 offset:15360
	ds_read_b64 v[144:145], v146 offset:15360
	ds_read_b64 v[146:147], v147 offset:15360
	s_waitcnt lgkmcnt(14)
; __device__ __forceinline__ float lane_get(float v, int src_lane) { return __builtin_bit_cast(float, __builtin_amdgcn_ds_bpermute(src_lane << 2, __builtin_bit_cast(int, v))); }
; __device__ __forceinline__ void dsa_attn_unit(const Ctx& c, int l, int b, int kvh, int qb64) {
;     ...
;             const unsigned wsh = mwd >> (4 * hf);
;             float mx = -INFINITY;
; #pragma unroll
;             for (int v = 0; v < 16; ++v) { const bool selv = (wsh >> ((v & 3) + 8 * (v >> 2))) & 1u; acc[v] = selv ? acc[v] * 0.12751743f : -INFINITY; mx = fmaxf(mx, acc[v]); }
;             mx = fmaxf(mx, lane_get(mx, lane ^ 32));
;             const float m_new = fmaxf(m_run, mx);
;             const float alpha = __builtin_amdgcn_exp2f(m_run - m_new);
;             float rs = 0.f;
; #pragma unroll
;             for (int v = 0; v < 16; ++v) { acc[v] = __builtin_amdgcn_exp2f(acc[v] - m_new); rs += acc[v]; }
;             rs += lane_get(rs, lane ^ 32);
;             l_run = l_run * alpha + rs; m_run = m_new;
;             if (__ballot(alpha != 1.0f) != 0ull) {
; #pragma unroll
;                 for (int mt = 0; mt < 4; ++mt)
; #pragma unroll
;                     for (int v = 0; v < 16; ++v) O[mt][v] *= alpha;
	v_mfma_f32_32x32x16_bf16 v[64:79], v[226:229], v[108:111], v[64:79]
	v_lshrrev_b32_e32 v175, v168, v175
	v_and_b32_e32 v223, 1, v175
	s_nop 9
	v_mul_f32_e32 v64, 0x3e0293ee, v64
	v_cmp_eq_u32_e32 vcc, 1, v223
	v_and_b32_e32 v223, 2, v175
	v_mul_f32_e32 v65, 0x3e0293ee, v65
	v_cndmask_b32_e32 v64, v180, v64, vcc
	v_cmp_ne_u32_e32 vcc, 0, v223
	v_and_b32_e32 v224, 4, v175
	v_mul_f32_e32 v66, 0x3e0293ee, v66
	v_cndmask_b32_e32 v65, v180, v65, vcc
	v_cmp_ne_u32_e32 vcc, 0, v224
	v_max3_f32 v223, v64, s60, v65
	v_mul_f32_e32 v68, 0x3e0293ee, v68
	v_cndmask_b32_e32 v224, v180, v66, vcc
	v_mul_f32_e32 v66, 0x3e0293ee, v67
	v_and_b32_e32 v67, 8, v175
	v_cmp_ne_u32_e32 vcc, 0, v67
	s_nop 1
	v_cndmask_b32_e32 v67, v180, v66, vcc
	v_max3_f32 v66, v223, v224, v67
	v_and_b32_e32 v223, 0x100, v175
	v_cmp_ne_u32_e32 vcc, 0, v223
	s_nop 1
	v_cndmask_b32_e32 v225, v180, v68, vcc
	v_mul_f32_e32 v68, 0x3e0293ee, v69
	v_and_b32_e32 v69, 0x200, v175
	v_cmp_ne_u32_e32 vcc, 0, v69
	v_and_b32_e32 v69, 0x400, v175
	s_nop 0
	v_cndmask_b32_e32 v226, v180, v68, vcc
	v_mul_f32_e32 v68, 0x3e0293ee, v70
	v_cmp_ne_u32_e32 vcc, 0, v69
	v_and_b32_e32 v69, 0x800, v175
	v_max3_f32 v66, v66, v225, v226
	v_cndmask_b32_e32 v70, v180, v68, vcc
	v_mul_f32_e32 v68, 0x3e0293ee, v71
	v_cmp_ne_u32_e32 vcc, 0, v69
	v_and_b32_e32 v69, 0x10000, v175
	s_nop 0
	v_cndmask_b32_e32 v227, v180, v68, vcc
	v_mul_f32_e32 v68, 0x3e0293ee, v72
	v_cmp_ne_u32_e32 vcc, 0, v69
	v_and_b32_e32 v69, 0x20000, v175
	v_max3_f32 v66, v66, v70, v227
	v_cndmask_b32_e32 v228, v180, v68, vcc
	v_mul_f32_e32 v68, 0x3e0293ee, v73
	v_cmp_ne_u32_e32 vcc, 0, v69
	v_and_b32_e32 v69, 0x40000, v175
	s_nop 0
	v_cndmask_b32_e32 v73, v180, v68, vcc
	v_mul_f32_e32 v68, 0x3e0293ee, v74
	v_cmp_ne_u32_e32 vcc, 0, v69
	v_and_b32_e32 v69, 0x80000, v175
	v_max3_f32 v66, v66, v228, v73
	v_cndmask_b32_e32 v74, v180, v68, vcc
	v_mul_f32_e32 v68, 0x3e0293ee, v75
	v_cmp_ne_u32_e32 vcc, 0, v69
	v_and_b32_e32 v69, 0x1000000, v175
	s_nop 0
	v_cndmask_b32_e32 v75, v180, v68, vcc
	v_mul_f32_e32 v68, 0x3e0293ee, v76
	v_cmp_ne_u32_e32 vcc, 0, v69
	v_and_b32_e32 v69, 0x2000000, v175
	v_max3_f32 v66, v66, v74, v75
	v_cndmask_b32_e32 v76, v180, v68, vcc
	v_mul_f32_e32 v68, 0x3e0293ee, v77
	v_cmp_ne_u32_e32 vcc, 0, v69
	v_and_b32_e32 v69, 0x4000000, v175
	s_nop 0
	v_cndmask_b32_e32 v229, v180, v68, vcc
	v_mul_f32_e32 v68, 0x3e0293ee, v78
	v_cmp_ne_u32_e32 vcc, 0, v69
	v_and_b32_e32 v69, 0x8000000, v175
	v_max3_f32 v66, v66, v76, v229
	v_cndmask_b32_e32 v230, v180, v68, vcc
	v_mul_f32_e32 v68, 0x3e0293ee, v79
	v_cmp_ne_u32_e32 vcc, 0, v69
	s_nop 1
	v_cndmask_b32_e32 v231, v180, v68, vcc
	v_max3_f32 v66, v66, v230, v231
	v_mov_b32_e32 v68, v66
	v_mov_b32_e32 v238, v66
	s_nop 1
	v_permlane32_swap_b32_e32 v68, v238
	s_waitcnt lgkmcnt(0)
	v_max3_f32 v223, v174, v68, v238
	v_sub_f32_e32 v64, v64, v223
	v_exp_f32_e32 v66, v64
	v_sub_f32_e32 v65, v65, v223
	v_exp_f32_e32 v68, v65
	v_sub_f32_e32 v65, v224, v223
	v_exp_f32_e32 v69, v65
	v_sub_f32_e32 v65, v67, v223
	v_exp_f32_e32 v71, v65
	v_sub_f32_e32 v65, v225, v223
	v_add_f32_e32 v77, 0, v66
	v_exp_f32_e32 v72, v65
	v_add_f32_e32 v65, v68, v77
	v_add_f32_e32 v65, v69, v65
	v_add_f32_e32 v65, v71, v65
	v_add_f32_e32 v67, v72, v65
	v_sub_f32_e32 v65, v226, v223
	v_exp_f32_e32 v77, v65
	v_sub_f32_e32 v65, v70, v223
	v_exp_f32_e32 v78, v65
	v_sub_f32_e32 v65, v227, v223
	v_sub_f32_e32 v64, v174, v223
	v_exp_f32_e32 v174, v65
	v_sub_f32_e32 v65, v228, v223
	v_exp_f32_e32 v65, v65
	v_add_f32_e32 v67, v77, v67
	v_add_f32_e32 v67, v78, v67
	v_add_f32_e32 v67, v174, v67
	v_add_f32_e32 v79, v65, v67
	v_sub_f32_e32 v67, v73, v223
	v_exp_f32_e32 v67, v67
	v_sub_f32_e32 v70, v74, v223
	v_exp_f32_e32 v70, v70
	v_sub_f32_e32 v73, v75, v223
	v_exp_f32_e32 v73, v73
	v_sub_f32_e32 v74, v76, v223
	v_exp_f32_e32 v74, v74
	v_sub_f32_e32 v76, v229, v223
	v_add_f32_e32 v75, v67, v79
	v_exp_f32_e32 v79, v76
	v_sub_f32_e32 v76, v230, v223
	v_add_f32_e32 v75, v70, v75
	v_exp_f32_e32 v175, v76
	v_sub_f32_e32 v76, v231, v223
	v_add_f32_e32 v75, v73, v75
	v_exp_f32_e32 v224, v76
	v_add_f32_e32 v75, v74, v75
	v_add_f32_e32 v75, v79, v75
	v_add_f32_e32 v75, v175, v75
	v_add_f32_e32 v75, v224, v75
	v_exp_f32_e32 v64, v64
	v_mov_b32_e32 v76, v75
	v_mov_b32_e32 v239, v75
	s_nop 1
	v_permlane32_swap_b32_e32 v76, v239
	v_cmp_neq_f32_e32 vcc, 1.0, v64
	s_cbranch_vccz .LBB0_2898
	v_pk_mul_f32 v[62:63], v[62:63], v[64:65] op_sel_hi:[1,0]
	v_pk_mul_f32 v[60:61], v[60:61], v[64:65] op_sel_hi:[1,0]
	v_pk_mul_f32 v[58:59], v[58:59], v[64:65] op_sel_hi:[1,0]
	v_pk_mul_f32 v[56:57], v[56:57], v[64:65] op_sel_hi:[1,0]
	v_pk_mul_f32 v[54:55], v[54:55], v[64:65] op_sel_hi:[1,0]
	v_pk_mul_f32 v[52:53], v[52:53], v[64:65] op_sel_hi:[1,0]
	v_pk_mul_f32 v[50:51], v[50:51], v[64:65] op_sel_hi:[1,0]
	v_pk_mul_f32 v[48:49], v[48:49], v[64:65] op_sel_hi:[1,0]
	v_pk_mul_f32 v[46:47], v[46:47], v[64:65] op_sel_hi:[1,0]
	v_pk_mul_f32 v[44:45], v[44:45], v[64:65] op_sel_hi:[1,0]
	v_pk_mul_f32 v[42:43], v[42:43], v[64:65] op_sel_hi:[1,0]
	v_pk_mul_f32 v[40:41], v[40:41], v[64:65] op_sel_hi:[1,0]
	v_pk_mul_f32 v[38:39], v[38:39], v[64:65] op_sel_hi:[1,0]
	v_pk_mul_f32 v[36:37], v[36:37], v[64:65] op_sel_hi:[1,0]
	v_pk_mul_f32 v[34:35], v[34:35], v[64:65] op_sel_hi:[1,0]
	v_pk_mul_f32 v[32:33], v[32:33], v[64:65] op_sel_hi:[1,0]
	v_pk_mul_f32 v[30:31], v[30:31], v[64:65] op_sel_hi:[1,0]
	v_pk_mul_f32 v[28:29], v[28:29], v[64:65] op_sel_hi:[1,0]
	v_pk_mul_f32 v[26:27], v[26:27], v[64:65] op_sel_hi:[1,0]
	v_pk_mul_f32 v[24:25], v[24:25], v[64:65] op_sel_hi:[1,0]
	v_pk_mul_f32 v[22:23], v[22:23], v[64:65] op_sel_hi:[1,0]
	v_pk_mul_f32 v[20:21], v[20:21], v[64:65] op_sel_hi:[1,0]
	v_pk_mul_f32 v[18:19], v[18:19], v[64:65] op_sel_hi:[1,0]
	v_pk_mul_f32 v[16:17], v[16:17], v[64:65] op_sel_hi:[1,0]
	v_pk_mul_f32 v[14:15], v[14:15], v[64:65] op_sel_hi:[1,0]
	v_pk_mul_f32 v[12:13], v[12:13], v[64:65] op_sel_hi:[1,0]
	v_pk_mul_f32 v[10:11], v[10:11], v[64:65] op_sel_hi:[1,0]
	v_pk_mul_f32 v[8:9], v[8:9], v[64:65] op_sel_hi:[1,0]
	v_pk_mul_f32 v[6:7], v[6:7], v[64:65] op_sel_hi:[1,0]
	v_pk_mul_f32 v[4:5], v[4:5], v[64:65] op_sel_hi:[1,0]
	v_pk_mul_f32 v[2:3], v[2:3], v[64:65] op_sel_hi:[1,0]
	v_pk_mul_f32 v[0:1], v[0:1], v[64:65] op_sel_hi:[1,0]
; __device__ __forceinline__ unsigned cvt_pk_bf16(float lo, float hi) { unsigned r; asm volatile("v_cvt_pk_bf16_f32 %0, %1, %2" : "=v"(r) : "v"(lo), "v"(hi)); return r; }
; __device__ __forceinline__ void dsa_attn_unit(const Ctx& c, int l, int b, int kvh, int qb64) {
;     ...
;             bf16x8 Pb[2];
; #pragma unroll
;             for (int s2 = 0; s2 < 2; ++s2) {
;                 const u32x4 t = {pg8::cvt_pk_bf16(acc[8 * s2 + 0], acc[8 * s2 + 1]), pg8::cvt_pk_bf16(acc[8 * s2 + 2], acc[8 * s2 + 3]), pg8::cvt_pk_bf16(acc[8 * s2 + 4], acc[8 * s2 + 5]), pg8::cvt_pk_bf16(acc[8 * s2 + 6], acc[8 * s2 + 7])};
;                 Pb[s2] = __builtin_bit_cast(bf16x8, t);
;             }
; #pragma unroll
;             for (int mt = 0; mt < 4; ++mt)
; #pragma unroll
;                 for (int s2 = 0; s2 < 2; ++s2) O[mt] = __builtin_amdgcn_mfma_f32_32x32x16_bf16(Vf[mt * 2 + s2], Pb[s2], O[mt], 0, 0, 0);
;         }
.LBB0_2898:
	v_cvt_pk_bf16_f32 v226, v66, v68
	v_cvt_pk_bf16_f32 v227, v69, v71
	v_cvt_pk_bf16_f32 v228, v72, v77
	v_cvt_pk_bf16_f32 v229, v78, v174
	v_cvt_pk_bf16_f32 v66, v65, v67
	v_cvt_pk_bf16_f32 v67, v70, v73
	v_cvt_pk_bf16_f32 v68, v74, v79
	v_cvt_pk_bf16_f32 v69, v175, v224
	s_waitcnt lgkmcnt(0)
	v_add_f32_e32 v65, v76, v239
	v_mfma_f32_32x32x16_bf16 v[48:63], v[132:135], v[226:229], v[48:63]
	v_fmac_f32_e32 v65, v213, v64
	v_mov_b32_e32 v213, v65
	v_mfma_f32_32x32x16_bf16 v[32:47], v[140:143], v[226:229], v[32:47]
	v_mfma_f32_32x32x16_bf16 v[16:31], v[152:155], v[226:229], v[16:31]
	v_mfma_f32_32x32x16_bf16 v[0:15], v[156:159], v[226:229], v[0:15]
	v_mfma_f32_32x32x16_bf16 v[48:63], v[128:131], v[66:69], v[48:63]
	v_mfma_f32_32x32x16_bf16 v[32:47], v[136:139], v[66:69], v[32:47]
	v_mfma_f32_32x32x16_bf16 v[16:31], v[148:151], v[66:69], v[16:31]
	v_mfma_f32_32x32x16_bf16 v[0:15], v[144:147], v[66:69], v[0:15]
	s_and_b64 vcc, exec, s[6:7]
	s_cbranch_vccz .LBB0_2889
	s_branch .LBB0_2888
